# same as previous plus generic (non-256-grid) fallback for the sample-unit K length restored
# speedup vs baseline: 1.0213x; 1.0005x over previous
.Lks_done:
	v_mov_b32_e32 v18, v182
	s_andn2_b64 vcc, exec, s[4:5]
	v_readfirstlane_b32 s13, v18
	s_cbranch_vccnz .LBB0_810
	v_lshlrev_b32_e32 v0, 4, v18
	v_add_u32_e32 v1, 0x2000, v0
	v_ashrrev_i32_e32 v2, 31, v1
	v_lshrrev_b32_e32 v2, 22, v2
	v_add_u32_e32 v2, v1, v2
	v_ashrrev_i32_e32 v2, 10, v2
	v_mul_i32_i24_e32 v3, 0x400, v2
	v_sub_u32_e32 v1, v1, v3
	v_lshrrev_b32_e32 v3, 4, v1
	v_bitop3_b32 v1, v3, v1, 32 bitop3:0x6c
	v_ashrrev_i32_e32 v3, 31, v1
	v_lshrrev_b32_e32 v3, 26, v3
	v_add_u32_e32 v3, v1, v3
	v_lshlrev_b32_e32 v5, 3, v2
	v_ashrrev_i32_e32 v4, 6, v3
	v_and_b32_e32 v5, -16, v5
	v_lshlrev_b32_e32 v2, 5, v2
	v_add_u32_e32 v5, v4, v5
	v_and_b32_e32 v12, 32, v2
	v_and_b32_e32 v2, 0xc0, v3
	v_and_b32_e32 v4, 3, v4
	s_mov_b32 s6, 0x7fffffe0
	v_lshrrev_b32_e32 v6, 2, v5
	v_lshlrev_b32_e32 v7, 1, v5
	v_sub_u32_e32 v1, v1, v2
	v_and_or_b32 v4, v5, s6, v4
	v_and_b32_e32 v6, 4, v6
	v_and_b32_e32 v7, 24, v7
	v_ashrrev_i16_sdwa v1, v186, sext(v1) dst_sel:DWORD dst_unused:UNUSED_PAD src0_sel:DWORD src1_sel:BYTE_0
	v_or3_b32 v4, v4, v6, v7
	v_bfe_i32 v13, v1, 0, 16
	v_mul_lo_u32 v4, v4, s12
	v_add_u32_e32 v1, v12, v13
	v_mul_lo_u32 v14, v5, s12
	v_add_lshl_u32 v128, v4, v1, 1
	v_add_lshl_u32 v130, v1, v14, 1
	v_bfe_i32 v1, v18, 27, 1
	v_lshrrev_b32_e32 v1, 22, v1
	v_add_u32_e32 v1, v0, v1
	v_and_b32_e32 v1, 0xfffffc00, v1
	v_sub_u32_e32 v0, v0, v1
	v_lshrrev_b32_e32 v1, 4, v0
	v_ashrrev_i32_e32 v3, 31, v18
	s_lshl_b32 s4, s12, 14
	v_bitop3_b32 v0, v1, v0, 32 bitop3:0x6c
	v_lshrrev_b32_e32 v3, 26, v3
	s_add_u32 s54, s34, s4
	v_ashrrev_i32_e32 v1, 31, v0
	v_add_u32_e32 v3, v18, v3
	v_readlane_b32 s8, v248, 24
	s_addc_u32 s55, s35, 0
	v_lshrrev_b32_e32 v1, 26, v1
	v_ashrrev_i32_e32 v3, 6, v3
	s_lshr_b32 s57, s12, 1
	v_readlane_b32 s9, v248, 28
	s_cmp_lg_u32 s9, 0
	s_cselect_b32 s57, 0x400, s57
	v_readlane_b32 s9, v248, 25
	s_mov_b32 s10, s8
	v_add_u32_e32 v1, v0, v1
	v_lshlrev_b32_e32 v4, 3, v3
	s_mul_i32 s9, s10, s57
	v_readlane_b32 s10, v248, 26
	s_ashr_i32 s4, s13, 6
	v_ashrrev_i32_e32 v2, 6, v1
	v_and_b32_e32 v4, -16, v4
	v_readlane_b32 s11, v248, 27
	s_mov_b32 s14, s10
	s_ashr_i32 s5, s13, 8
	s_lshl_b32 s56, s4, 10
	v_add_u32_e32 v4, v2, v4
	v_and_b32_e32 v1, 0xc0, v1
	s_mul_i32 s11, s53, s14
	v_and_b32_e32 v2, 3, v2
	v_lshrrev_b32_e32 v5, 2, v4
	v_lshlrev_b32_e32 v6, 1, v4
	v_sub_u32_e32 v0, v0, v1
	s_mul_hi_i32 s10, s53, s10
	s_add_u32 s11, s18, s11
	v_and_or_b32 v2, v4, s6, v2
	v_and_b32_e32 v5, 4, v5
	v_and_b32_e32 v6, 24, v6
	v_lshlrev_b32_e32 v3, 5, v3
	v_ashrrev_i16_sdwa v0, v186, sext(v0) dst_sel:DWORD dst_unused:UNUSED_PAD src0_sel:DWORD src1_sel:BYTE_0
	s_addc_u32 s10, s52, s10
	v_or3_b32 v2, v2, v5, v6
	v_and_b32_e32 v15, 32, v3
	v_bfe_i32 v16, v0, 0, 16
	s_mul_hi_i32 s8, s8, s57
	s_add_u32 s36, s11, s9
	v_mul_lo_u32 v2, v2, s12
	v_add_u32_e32 v0, v15, v16
	s_addc_u32 s37, s10, s8
	s_add_i32 s66, s56, 0
	v_add_lshl_u32 v144, v2, v0, 1
	v_readlane_b32 s7, v248, 23
	s_add_i32 m0, s66, 0x10000
	s_mul_hi_i32 s6, s53, s7
	s_mul_i32 s7, s53, s7
	global_load_lds_dwordx4 v144, s[36:37]
	s_add_i32 m0, s66, 0x12000
	s_add_u32 s7, s54, s7
	s_addc_u32 s6, s55, s6
	v_mul_lo_u32 v17, v4, s12
	s_add_u32 s34, s7, s9
	v_add_lshl_u32 v132, v0, v17, 1
	global_load_lds_dwordx4 v128, s[36:37]
	s_addc_u32 s35, s6, s8
	s_mov_b32 m0, s66
	s_add_i32 s67, s66, 0x2000
	global_load_lds_dwordx4 v132, s[34:35]
	s_mov_b32 m0, s67
	s_add_u32 s6, s36, s76
	global_load_lds_dwordx4 v130, s[34:35]
	s_addc_u32 s7, s37, 0
	s_add_i32 m0, s66, 0x14000
	v_mov_b32_e32 v129, v145
	global_load_lds_dwordx4 v144, s[6:7]
	s_add_i32 m0, s66, 0x16000
	v_lshl_add_u64 v[8:9], s[6:7], 0, v[144:145]
	v_lshl_add_u64 v[10:11], s[6:7], 0, v[128:129]
	global_load_lds_dwordx4 v128, s[6:7]
	s_add_u32 s6, s34, s76
	s_addc_u32 s7, s35, 0
	s_add_i32 s70, s66, 0x4000
	s_mov_b32 m0, s70
	s_add_i32 s71, s66, 0x6000
	global_load_lds_dwordx4 v132, s[6:7]
	s_mov_b32 m0, s71
	v_mov_b32_e32 v133, v145
	global_load_lds_dwordx4 v130, s[6:7]
	v_mov_b32_e32 v131, v145
	v_lshl_add_u64 v[0:1], s[36:37], 0, v[144:145]
	v_lshl_add_u64 v[2:3], s[36:37], 0, v[128:129]
	v_lshl_add_u64 v[4:5], s[34:35], 0, v[132:133]
	v_lshl_add_u64 v[6:7], s[34:35], 0, v[130:131]
	s_cmp_lg_u32 s5, 1
	s_cbranch_scc1 .LBB0_781
	s_barrier
.LBB0_781:
	v_readlane_b32 s16, v248, 28
	s_cmp_lg_u32 s16, 0
	s_mov_b32 s16, 0x1a3a0000
	s_cselect_b32 s16, 0x13b80000, s16
	s_add_u32 s6, s26, 0x1a5a0000
	s_addc_u32 s7, s27, 0
	s_add_u32 s8, s26, 0x1a7a0000
	s_addc_u32 s9, s27, 0
	v_lshrrev_b32_e32 v20, 1, v18
	s_add_u32 s10, s26, 0x1a9a0000
	v_and_b32_e32 v20, 24, v20
	s_addc_u32 s11, s27, 0
	v_and_b32_e32 v19, 15, v18
	v_lshlrev_b32_e32 v21, 1, v20
	v_lshlrev_b32_e32 v18, 2, v18
	s_lshl_b32 s4, s4, 5
	v_lshl_or_b32 v140, s5, 6, v19
	v_lshl_or_b32 v19, v19, 6, v21
	s_lshl_b32 s5, s5, 13
	v_and_b32_e32 v18, 32, v18
	s_and_b32 s4, s4, 0x60
	s_lshr_b32 s12, s12, 8
	v_readlane_b32 s17, v248, 28
	s_cmp_lg_u32 s17, 0
	s_cselect_b32 s12, 8, s12
	v_bitop3_b32 v21, v19, s5, v18 bitop3:0xde
	s_lshl_b32 s5, s4, 7
	s_add_u32 s16, s26, s16
	s_addc_u32 s17, s27, 0
	s_add_i32 m0, s66, 0x18000
	v_lshl_add_u64 v[0:1], v[0:1], 0, s[86:87]
	s_waitcnt vmcnt(4)
	s_barrier
	global_load_lds_dwordx4 v[0:1], off
	v_lshl_add_u64 v[0:1], v[2:3], 0, s[86:87]
	s_add_i32 m0, s66, 0x1a000
	s_add_i32 s72, s66, 0x8000
	global_load_lds_dwordx4 v[0:1], off
	v_lshl_add_u64 v[0:1], v[4:5], 0, s[86:87]
	s_mov_b32 m0, s72
	s_add_i32 s73, s66, 0xa000
	global_load_lds_dwordx4 v[0:1], off
	v_lshl_add_u64 v[0:1], v[6:7], 0, s[86:87]
	s_mov_b32 m0, s73
	v_bitop3_b32 v141, v19, s5, v18 bitop3:0xde
	global_load_lds_dwordx4 v[0:1], off
	s_add_i32 m0, s66, 0x1c000
	v_lshl_add_u64 v[0:1], v[8:9], 0, s[86:87]
	global_load_lds_dwordx4 v[0:1], off
	v_lshl_add_u64 v[0:1], v[10:11], 0, s[86:87]
	s_add_i32 m0, s66, 0x1e000
	s_add_i32 s74, s12, -2
	global_load_lds_dwordx4 v[0:1], off
	v_add_u32_e32 v0, v17, v15
	v_add_lshl_u32 v0, v0, v16, 1
	v_mov_b32_e32 v1, v145
	s_waitcnt vmcnt(6)
	v_lshl_add_u64 v[134:135], s[76:77], 0, v[0:1]
	v_add_u32_e32 v0, v14, v12
	v_add_lshl_u32 v0, v0, v13, 1
	v_or_b32_e32 v142, s4, v20
	v_lshl_add_u64 v[136:137], s[76:77], 0, v[0:1]
	s_mov_b32 s75, 0
	v_add_u32_e32 v143, 0, v21
	v_readlane_b32 s88, v248, 22
	v_readlane_b32 s89, v248, 23
	s_barrier
	s_branch .LBB0_783
